# baseline (speedup 1.0000x reference)
.LBB0_159:
	s_lshl_b32 s2, s0, 1
	s_and_b32 s12, s2, 0x700
	s_ashr_i32 s2, s94, 7
	v_writelane_b32 v255, s0, 6
	s_ashr_i32 s3, s2, 31
	s_bfe_u32 s90, s94, 0x40003
	s_lshl_b64 s[86:87], s[2:3], 12
	s_mul_hi_i32 s3, s2, 0x1800000
	s_mul_i32 s2, s2, 0x1800000
	v_readlane_b32 s0, v255, 2
	s_add_u32 s8, s0, s2
	v_readlane_b32 s0, v255, 3
	s_addc_u32 s9, s0, s3
	s_lshl_b32 s10, s94, 8
	s_xor_b32 s91, s90, 31
	s_and_b32 s74, s10, 0x700
	v_writelane_b32 v255, s94, 7
	s_add_u32 s10, s8, s74
	s_addc_u32 s11, s9, 0
	v_readlane_b32 s0, v255, 4
	s_add_u32 s10, s10, s0
	v_lshl_add_u64 v[2:3], s[8:9], 0, v[132:133]
	s_addc_u32 s11, s11, 0
	v_mov_b32_e32 v173, v0
	v_lshl_add_u64 v[2:3], v[2:3], 0, s[74:75]
	v_mov_b32_e32 v175, v0
	v_lshl_add_u64 v[176:177], s[10:11], 0, v[172:173]
	v_lshl_add_u64 v[2:3], v[2:3], 0, v[174:175]
	s_mov_b64 s[0:1], 0x800
	s_mov_b64 s[10:11], 0x30800
	s_mov_b64 s[14:15], 0x31000
	v_lshl_add_u64 v[178:179], v[2:3], 0, s[0:1]
	v_lshl_add_u64 v[180:181], v[2:3], 0, s[10:11]
	v_lshl_add_u64 v[182:183], v[2:3], 0, s[14:15]
	v_lshl_add_u64 v[2:3], s[8:9], 0, v[134:135]
	v_lshl_add_u64 v[2:3], v[2:3], 0, s[74:75]
	v_lshl_add_u64 v[2:3], v[2:3], 0, v[174:175]
	v_lshl_add_u64 v[184:185], v[2:3], 0, s[0:1]
	v_lshl_add_u64 v[186:187], v[2:3], 0, s[10:11]
	v_lshl_add_u64 v[188:189], v[2:3], 0, s[14:15]
	v_lshl_add_u64 v[2:3], s[8:9], 0, v[136:137]
	v_lshl_add_u64 v[2:3], v[2:3], 0, s[74:75]
	v_lshl_add_u64 v[2:3], v[2:3], 0, v[174:175]
	s_or_b32 s2, s2, s12
	v_lshl_add_u64 v[190:191], v[2:3], 0, s[0:1]
	v_lshl_add_u64 v[192:193], v[2:3], 0, s[10:11]
	v_lshl_add_u64 v[194:195], v[2:3], 0, s[14:15]
	v_lshl_add_u64 v[196:197], v[138:139], 0, s[74:75]
	v_and_b32_e32 v212, 1, v209
	v_mul_u32_u24_e32 v212, 62, v212
	v_mov_b32_e32 v213, v0
	v_lshl_add_u64 v[196:197], v[196:197], 0, v[212:213]
	v_lshl_add_u64 v[198:199], v[170:171], 0, s[2:3]
	s_mov_b64 s[8:9], -1
	s_branch .LBB0_162

.LBB0_212:
	s_andn2_b64 vcc, exec, s[82:83]
	s_waitcnt lgkmcnt(0)
	s_barrier
	s_cbranch_vccnz .LBB0_161
	ds_read2_b32 v[98:99], v163 offset1:32
	ds_read2_b32 v[102:103], v163 offset0:64 offset1:96
	v_mov_b32_e32 v100, v50
	v_mov_b32_e32 v101, v34
	v_mov_b32_e32 v104, v18
	s_waitcnt lgkmcnt(1)
	v_pk_fma_f32 v[98:99], v[100:101], v[96:97], v[98:99] op_sel_hi:[1,0,1] neg_lo:[0,0,1] neg_hi:[0,0,1]
	v_mov_b32_e32 v105, v2
	v_pk_mul_f32 v[100:101], v[98:99], v[98:99]
	s_waitcnt lgkmcnt(0)
	v_pk_fma_f32 v[96:97], v[104:105], v[96:97], v[102:103] op_sel_hi:[1,0,1] neg_lo:[0,0,1] neg_hi:[0,0,1]
	v_add_f32_e32 v1, v100, v101
	v_pk_mul_f32 v[102:103], v[96:97], v[96:97]
	s_ashr_i32 s8, s74, 31
	v_add_f32_e32 v1, v1, v102
	v_add_f32_e32 v1, v1, v103
	s_add_u32 s10, s86, s74
	s_addc_u32 s11, s87, s8
	v_mov_b32_e32 v101, s11
	v_or_b32_e32 v100, s10, v130
	s_waitcnt lgkmcnt(0)
	s_nop 1
	v_add_f32_dpp v1, v1, v1 quad_perm:[1,0,3,2] row_mask:0xf bank_mask:0xf
	v_lshlrev_b64 v[100:101], 11, v[100:101]
	v_lshl_add_u64 v[100:101], v[196:197], 0, v[100:101]
	s_waitcnt lgkmcnt(0)
	s_nop 1
	v_add_f32_dpp v1, v1, v1 quad_perm:[2,3,0,1] row_mask:0xf bank_mask:0xf
	s_waitcnt lgkmcnt(0)
	s_nop 1
	v_add_f32_dpp v1, v1, v1 row_half_mirror row_mask:0xf bank_mask:0xf
	s_waitcnt lgkmcnt(0)
	s_nop 1
	v_add_f32_dpp v1, v1, v1 row_mirror row_mask:0xf bank_mask:0xf
	ds_bpermute_b32 v2, v147, v1
	s_waitcnt lgkmcnt(0)
	v_add_f32_e32 v1, v1, v2
	v_fmamk_f32 v1, v1, 0x3c000000, v208
	v_cmp_gt_f32_e32 vcc, s95, v1
	v_mul_f32_e32 v2, 0x4b800000, v1
	s_nop 0
	v_cndmask_b32_e32 v1, v1, v2, vcc
	v_rsq_f32_e32 v1, v1
	s_nop 0
	v_mul_f32_e32 v2, 0x45800000, v1
	v_cndmask_b32_e32 v1, v1, v2, vcc
	v_mul_f32_e32 v212, v98, v1
	v_mul_f32_e32 v213, v99, v1
	s_nop 1
	v_mov_b32_dpp v214, v212 quad_perm:[1,0,3,2] row_mask:0xf bank_mask:0xf
	v_mov_b32_dpp v215, v213 quad_perm:[1,0,3,2] row_mask:0xf bank_mask:0xf
	v_cndmask_b32_e64 v212, v215, v212, s[6:7]
	v_cndmask_b32_e64 v213, v213, v214, s[6:7]
	v_cvt_pk_bf16_f32 v212, v212, v213
	global_store_dword v[100:101], v212, off
	v_mul_f32_e32 v213, v96, v1
	v_mul_f32_e32 v214, v97, v1
	s_nop 1
	v_mov_b32_dpp v215, v213 quad_perm:[1,0,3,2] row_mask:0xf bank_mask:0xf
	v_mov_b32_dpp v212, v214 quad_perm:[1,0,3,2] row_mask:0xf bank_mask:0xf
	v_cndmask_b32_e64 v213, v212, v213, s[6:7]
	v_cndmask_b32_e64 v214, v214, v215, s[6:7]
	v_cvt_pk_bf16_f32 v213, v213, v214
	global_store_dword v[100:101], v213, off offset:128
	ds_read2_b32 v[96:97], v165 offset1:32
	ds_read2_b32 v[98:99], v165 offset0:64 offset1:96
	v_mov_b32_e32 v34, v51
	s_waitcnt lgkmcnt(2)
	v_mov_b32_e32 v2, v19
	s_waitcnt lgkmcnt(1)
	v_pk_fma_f32 v[18:19], v[34:35], v[94:95], v[96:97] op_sel_hi:[1,0,1] neg_lo:[0,0,1] neg_hi:[0,0,1]
	s_waitcnt lgkmcnt(0)
	v_pk_fma_f32 v[2:3], v[2:3], v[94:95], v[98:99] op_sel_hi:[1,0,1] neg_lo:[0,0,1] neg_hi:[0,0,1]
	v_pk_mul_f32 v[34:35], v[18:19], v[18:19]
	v_pk_mul_f32 v[50:51], v[2:3], v[2:3]
	v_add_f32_e32 v1, v34, v35
	v_add_f32_e32 v1, v1, v50
	v_add_f32_e32 v1, v1, v51
	v_mov_b32_e32 v35, s11
	s_waitcnt lgkmcnt(0)
	s_nop 1
	v_add_f32_dpp v1, v1, v1 quad_perm:[1,0,3,2] row_mask:0xf bank_mask:0xf
	s_waitcnt lgkmcnt(0)
	s_nop 1
	v_add_f32_dpp v1, v1, v1 quad_perm:[2,3,0,1] row_mask:0xf bank_mask:0xf
	s_waitcnt lgkmcnt(0)
	s_nop 1
	v_add_f32_dpp v1, v1, v1 row_half_mirror row_mask:0xf bank_mask:0xf
	s_waitcnt lgkmcnt(0)
	s_nop 1
	v_add_f32_dpp v1, v1, v1 row_mirror row_mask:0xf bank_mask:0xf
	ds_bpermute_b32 v34, v147, v1
	s_waitcnt lgkmcnt(0)
	v_add_f32_e32 v1, v1, v34
	v_fmamk_f32 v1, v1, 0x3c000000, v208
	v_mul_f32_e32 v34, 0x4b800000, v1
	v_cmp_gt_f32_e32 vcc, s95, v1
	s_nop 1
	v_cndmask_b32_e32 v1, v1, v34, vcc
	v_rsq_f32_e32 v1, v1
	s_nop 0
	v_mul_f32_e32 v34, 0x45800000, v1
	v_cndmask_b32_e32 v1, v1, v34, vcc
	v_or_b32_e32 v34, s10, v140
	v_lshlrev_b64 v[34:35], 11, v[34:35]
	v_lshl_add_u64 v[34:35], v[196:197], 0, v[34:35]
	v_mul_f32_e32 v212, v18, v1
	v_mul_f32_e32 v213, v19, v1
	s_nop 1
	v_mov_b32_dpp v214, v212 quad_perm:[1,0,3,2] row_mask:0xf bank_mask:0xf
	v_mov_b32_dpp v215, v213 quad_perm:[1,0,3,2] row_mask:0xf bank_mask:0xf
	v_cndmask_b32_e64 v212, v215, v212, s[6:7]
	v_cndmask_b32_e64 v213, v213, v214, s[6:7]
	v_cvt_pk_bf16_f32 v212, v212, v213
	global_store_dword v[34:35], v212, off
	v_mul_f32_e32 v213, v2, v1
	v_mul_f32_e32 v214, v3, v1
	s_nop 1
	v_mov_b32_dpp v215, v213 quad_perm:[1,0,3,2] row_mask:0xf bank_mask:0xf
	v_mov_b32_dpp v212, v214 quad_perm:[1,0,3,2] row_mask:0xf bank_mask:0xf
	v_cndmask_b32_e64 v213, v212, v213, s[6:7]
	v_cndmask_b32_e64 v214, v214, v215, s[6:7]
	v_cvt_pk_bf16_f32 v213, v213, v214
	global_store_dword v[34:35], v213, off offset:128
	s_waitcnt lgkmcnt(0)
	ds_read2_b32 v[2:3], v167 offset1:32
	ds_read2_b32 v[34:35], v167 offset0:64 offset1:96
	v_mov_b32_e32 v18, v52
	v_mov_b32_e32 v19, v36
	v_mov_b32_e32 v50, v20
	s_waitcnt lgkmcnt(1)
	v_pk_fma_f32 v[18:19], v[18:19], v[92:93], v[2:3] op_sel_hi:[1,0,1] neg_lo:[0,0,1] neg_hi:[0,0,1]
	v_mov_b32_e32 v51, v4
	v_pk_mul_f32 v[94:95], v[18:19], v[18:19]
	s_waitcnt lgkmcnt(0)
	v_pk_fma_f32 v[2:3], v[50:51], v[92:93], v[34:35] op_sel_hi:[1,0,1] neg_lo:[0,0,1] neg_hi:[0,0,1]
	v_add_f32_e32 v1, v94, v95
	v_pk_mul_f32 v[34:35], v[2:3], v[2:3]
	s_nop 0
	v_add_f32_e32 v1, v1, v34
	v_add_f32_e32 v1, v1, v35
	v_mov_b32_e32 v35, s11
	v_or_b32_e32 v34, s10, v142
	v_lshlrev_b64 v[34:35], 11, v[34:35]
	v_lshl_add_u64 v[34:35], v[196:197], 0, v[34:35]
	s_waitcnt lgkmcnt(0)
	s_nop 1
	v_add_f32_dpp v1, v1, v1 quad_perm:[1,0,3,2] row_mask:0xf bank_mask:0xf
	s_waitcnt lgkmcnt(0)
	s_nop 1
	v_add_f32_dpp v1, v1, v1 quad_perm:[2,3,0,1] row_mask:0xf bank_mask:0xf
	s_waitcnt lgkmcnt(0)
	s_nop 1
	v_add_f32_dpp v1, v1, v1 row_half_mirror row_mask:0xf bank_mask:0xf
	s_waitcnt lgkmcnt(0)
	s_nop 1
	v_add_f32_dpp v1, v1, v1 row_mirror row_mask:0xf bank_mask:0xf
	ds_bpermute_b32 v4, v147, v1
	s_waitcnt lgkmcnt(0)
	v_add_f32_e32 v1, v1, v4
	v_fmamk_f32 v1, v1, 0x3c000000, v208
	v_mul_f32_e32 v4, 0x4b800000, v1
	v_cmp_gt_f32_e32 vcc, s95, v1
	s_nop 1
	v_cndmask_b32_e32 v1, v1, v4, vcc
	v_rsq_f32_e32 v1, v1
	s_nop 0
	v_mul_f32_e32 v4, 0x45800000, v1
	v_cndmask_b32_e32 v1, v1, v4, vcc
	v_mul_f32_e32 v212, v18, v1
	v_mul_f32_e32 v213, v19, v1
	s_nop 1
	v_mov_b32_dpp v214, v212 quad_perm:[1,0,3,2] row_mask:0xf bank_mask:0xf
	v_mov_b32_dpp v215, v213 quad_perm:[1,0,3,2] row_mask:0xf bank_mask:0xf
	v_cndmask_b32_e64 v212, v215, v212, s[6:7]
	v_cndmask_b32_e64 v213, v213, v214, s[6:7]
	v_cvt_pk_bf16_f32 v212, v212, v213
	global_store_dword v[34:35], v212, off
	v_mul_f32_e32 v213, v2, v1
	v_mul_f32_e32 v214, v3, v1
	s_nop 1
	v_mov_b32_dpp v215, v213 quad_perm:[1,0,3,2] row_mask:0xf bank_mask:0xf
	v_mov_b32_dpp v212, v214 quad_perm:[1,0,3,2] row_mask:0xf bank_mask:0xf
	v_cndmask_b32_e64 v213, v212, v213, s[6:7]
	v_cndmask_b32_e64 v214, v214, v215, s[6:7]
	v_cvt_pk_bf16_f32 v213, v213, v214
	global_store_dword v[34:35], v213, off offset:128
	s_waitcnt lgkmcnt(0)
	ds_read2_b32 v[2:3], v169 offset1:32
	ds_read2_b32 v[34:35], v169 offset0:64 offset1:96
	v_mov_b32_e32 v36, v53
	v_mov_b32_e32 v4, v21
	s_waitcnt lgkmcnt(1)
	v_pk_fma_f32 v[18:19], v[36:37], v[90:91], v[2:3] op_sel_hi:[1,0,1] neg_lo:[0,0,1] neg_hi:[0,0,1]
	s_waitcnt lgkmcnt(0)
	v_pk_fma_f32 v[2:3], v[4:5], v[90:91], v[34:35] op_sel_hi:[1,0,1] neg_lo:[0,0,1] neg_hi:[0,0,1]
	v_pk_mul_f32 v[4:5], v[18:19], v[18:19]
	v_pk_mul_f32 v[20:21], v[2:3], v[2:3]
	v_add_f32_e32 v1, v4, v5
	v_add_f32_e32 v1, v1, v20
	v_add_f32_e32 v1, v1, v21
	v_mov_b32_e32 v5, s11
	s_waitcnt lgkmcnt(0)
	s_nop 1
	v_add_f32_dpp v1, v1, v1 quad_perm:[1,0,3,2] row_mask:0xf bank_mask:0xf
	s_waitcnt lgkmcnt(0)
	s_nop 1
	v_add_f32_dpp v1, v1, v1 quad_perm:[2,3,0,1] row_mask:0xf bank_mask:0xf
	s_waitcnt lgkmcnt(0)
	s_nop 1
	v_add_f32_dpp v1, v1, v1 row_half_mirror row_mask:0xf bank_mask:0xf
	s_waitcnt lgkmcnt(0)
	s_nop 1
	v_add_f32_dpp v1, v1, v1 row_mirror row_mask:0xf bank_mask:0xf
	ds_bpermute_b32 v4, v147, v1
	s_waitcnt lgkmcnt(0)
	v_add_f32_e32 v1, v1, v4
	v_fmamk_f32 v1, v1, 0x3c000000, v208
	v_mul_f32_e32 v4, 0x4b800000, v1
	v_cmp_gt_f32_e32 vcc, s95, v1
	s_nop 1
	v_cndmask_b32_e32 v1, v1, v4, vcc
	v_rsq_f32_e32 v1, v1
	s_nop 0
	v_mul_f32_e32 v4, 0x45800000, v1
	v_cndmask_b32_e32 v1, v1, v4, vcc
	v_or_b32_e32 v4, s10, v144
	v_lshlrev_b64 v[4:5], 11, v[4:5]
	v_lshl_add_u64 v[4:5], v[196:197], 0, v[4:5]
	v_mul_f32_e32 v212, v18, v1
	v_mul_f32_e32 v213, v19, v1
	s_nop 1
	v_mov_b32_dpp v214, v212 quad_perm:[1,0,3,2] row_mask:0xf bank_mask:0xf
	v_mov_b32_dpp v215, v213 quad_perm:[1,0,3,2] row_mask:0xf bank_mask:0xf
	v_cndmask_b32_e64 v212, v215, v212, s[6:7]
	v_cndmask_b32_e64 v213, v213, v214, s[6:7]
	v_cvt_pk_bf16_f32 v212, v212, v213
	global_store_dword v[4:5], v212, off
	v_mul_f32_e32 v213, v2, v1
	v_mul_f32_e32 v214, v3, v1
	s_nop 1
	v_mov_b32_dpp v215, v213 quad_perm:[1,0,3,2] row_mask:0xf bank_mask:0xf
	v_mov_b32_dpp v212, v214 quad_perm:[1,0,3,2] row_mask:0xf bank_mask:0xf
	v_cndmask_b32_e64 v213, v212, v213, s[6:7]
	v_cndmask_b32_e64 v214, v214, v215, s[6:7]
	v_cvt_pk_bf16_f32 v213, v213, v214
	global_store_dword v[4:5], v213, off offset:128
	s_waitcnt lgkmcnt(0)
	ds_read2_b32 v[2:3], v202 offset1:32
	ds_read2_b32 v[18:19], v202 offset0:64 offset1:96
	v_mov_b32_e32 v4, v54
	v_mov_b32_e32 v5, v38
	v_mov_b32_e32 v20, v22
	s_waitcnt lgkmcnt(1)
	v_pk_fma_f32 v[4:5], v[4:5], v[88:89], v[2:3] op_sel_hi:[1,0,1] neg_lo:[0,0,1] neg_hi:[0,0,1]
	v_mov_b32_e32 v21, v6
	v_pk_mul_f32 v[34:35], v[4:5], v[4:5]
	s_waitcnt lgkmcnt(0)
	v_pk_fma_f32 v[2:3], v[20:21], v[88:89], v[18:19] op_sel_hi:[1,0,1] neg_lo:[0,0,1] neg_hi:[0,0,1]
	v_add_f32_e32 v1, v34, v35
	v_pk_mul_f32 v[18:19], v[2:3], v[2:3]
	s_nop 0
	v_add_f32_e32 v1, v1, v18
	v_add_f32_e32 v1, v1, v19
	v_mov_b32_e32 v19, s11
	v_or_b32_e32 v18, s10, v146
	v_lshlrev_b64 v[18:19], 11, v[18:19]
	v_lshl_add_u64 v[18:19], v[196:197], 0, v[18:19]
	s_waitcnt lgkmcnt(0)
	s_nop 1
	v_add_f32_dpp v1, v1, v1 quad_perm:[1,0,3,2] row_mask:0xf bank_mask:0xf
	s_waitcnt lgkmcnt(0)
	s_nop 1
	v_add_f32_dpp v1, v1, v1 quad_perm:[2,3,0,1] row_mask:0xf bank_mask:0xf
	s_waitcnt lgkmcnt(0)
	s_nop 1
	v_add_f32_dpp v1, v1, v1 row_half_mirror row_mask:0xf bank_mask:0xf
	s_waitcnt lgkmcnt(0)
	s_nop 1
	v_add_f32_dpp v1, v1, v1 row_mirror row_mask:0xf bank_mask:0xf
	ds_bpermute_b32 v6, v147, v1
	s_waitcnt lgkmcnt(0)
	v_add_f32_e32 v1, v1, v6
	v_fmamk_f32 v1, v1, 0x3c000000, v208
	v_mul_f32_e32 v6, 0x4b800000, v1
	v_cmp_gt_f32_e32 vcc, s95, v1
	s_nop 1
	v_cndmask_b32_e32 v1, v1, v6, vcc
	v_rsq_f32_e32 v1, v1
	s_nop 0
	v_mul_f32_e32 v6, 0x45800000, v1
	v_cndmask_b32_e32 v1, v1, v6, vcc
	v_mul_f32_e32 v212, v4, v1
	v_mul_f32_e32 v213, v5, v1
	s_nop 1
	v_mov_b32_dpp v214, v212 quad_perm:[1,0,3,2] row_mask:0xf bank_mask:0xf
	v_mov_b32_dpp v215, v213 quad_perm:[1,0,3,2] row_mask:0xf bank_mask:0xf
	v_cndmask_b32_e64 v212, v215, v212, s[6:7]
	v_cndmask_b32_e64 v213, v213, v214, s[6:7]
	v_cvt_pk_bf16_f32 v212, v212, v213
	global_store_dword v[18:19], v212, off
	v_mul_f32_e32 v213, v2, v1
	v_mul_f32_e32 v214, v3, v1
	s_nop 1
	v_mov_b32_dpp v215, v213 quad_perm:[1,0,3,2] row_mask:0xf bank_mask:0xf
	v_mov_b32_dpp v212, v214 quad_perm:[1,0,3,2] row_mask:0xf bank_mask:0xf
	v_cndmask_b32_e64 v213, v212, v213, s[6:7]
	v_cndmask_b32_e64 v214, v214, v215, s[6:7]
	v_cvt_pk_bf16_f32 v213, v213, v214
	global_store_dword v[18:19], v213, off offset:128
	s_waitcnt lgkmcnt(0)
	ds_read2_b32 v[2:3], v203 offset1:32
	ds_read2_b32 v[18:19], v203 offset0:64 offset1:96
	v_mov_b32_e32 v38, v55
	v_mov_b32_e32 v6, v23
	s_waitcnt lgkmcnt(1)
	v_pk_fma_f32 v[4:5], v[38:39], v[86:87], v[2:3] op_sel_hi:[1,0,1] neg_lo:[0,0,1] neg_hi:[0,0,1]
	s_waitcnt lgkmcnt(0)
	v_pk_fma_f32 v[2:3], v[6:7], v[86:87], v[18:19] op_sel_hi:[1,0,1] neg_lo:[0,0,1] neg_hi:[0,0,1]
	v_pk_mul_f32 v[6:7], v[4:5], v[4:5]
	v_pk_mul_f32 v[18:19], v[2:3], v[2:3]
	v_add_f32_e32 v1, v6, v7
	v_add_f32_e32 v1, v1, v18
	v_add_f32_e32 v1, v1, v19
	v_mov_b32_e32 v7, s11
	s_waitcnt lgkmcnt(0)
	s_nop 1
	v_add_f32_dpp v1, v1, v1 quad_perm:[1,0,3,2] row_mask:0xf bank_mask:0xf
	s_waitcnt lgkmcnt(0)
	s_nop 1
	v_add_f32_dpp v1, v1, v1 quad_perm:[2,3,0,1] row_mask:0xf bank_mask:0xf
	s_waitcnt lgkmcnt(0)
	s_nop 1
	v_add_f32_dpp v1, v1, v1 row_half_mirror row_mask:0xf bank_mask:0xf
	s_waitcnt lgkmcnt(0)
	s_nop 1
	v_add_f32_dpp v1, v1, v1 row_mirror row_mask:0xf bank_mask:0xf
	ds_bpermute_b32 v6, v147, v1
	s_waitcnt lgkmcnt(0)
	v_add_f32_e32 v1, v1, v6
	v_fmamk_f32 v1, v1, 0x3c000000, v208
	v_mul_f32_e32 v6, 0x4b800000, v1
	v_cmp_gt_f32_e32 vcc, s95, v1
	s_nop 1
	v_cndmask_b32_e32 v1, v1, v6, vcc
	v_rsq_f32_e32 v1, v1
	s_nop 0
	v_mul_f32_e32 v6, 0x45800000, v1
	v_cndmask_b32_e32 v1, v1, v6, vcc
	v_or_b32_e32 v6, s10, v148
	v_lshlrev_b64 v[6:7], 11, v[6:7]
	v_lshl_add_u64 v[6:7], v[196:197], 0, v[6:7]
	v_mul_f32_e32 v212, v4, v1
	v_mul_f32_e32 v213, v5, v1
	s_nop 1
	v_mov_b32_dpp v214, v212 quad_perm:[1,0,3,2] row_mask:0xf bank_mask:0xf
	v_mov_b32_dpp v215, v213 quad_perm:[1,0,3,2] row_mask:0xf bank_mask:0xf
	v_cndmask_b32_e64 v212, v215, v212, s[6:7]
	v_cndmask_b32_e64 v213, v213, v214, s[6:7]
	v_cvt_pk_bf16_f32 v212, v212, v213
	global_store_dword v[6:7], v212, off
	v_mul_f32_e32 v213, v2, v1
	v_mul_f32_e32 v214, v3, v1
	s_nop 1
	v_mov_b32_dpp v215, v213 quad_perm:[1,0,3,2] row_mask:0xf bank_mask:0xf
	v_mov_b32_dpp v212, v214 quad_perm:[1,0,3,2] row_mask:0xf bank_mask:0xf
	v_cndmask_b32_e64 v213, v212, v213, s[6:7]
	v_cndmask_b32_e64 v214, v214, v215, s[6:7]
	v_cvt_pk_bf16_f32 v213, v213, v214
	global_store_dword v[6:7], v213, off offset:128
	s_waitcnt lgkmcnt(0)
	ds_read2_b32 v[2:3], v204 offset1:32
	ds_read2_b32 v[6:7], v204 offset0:64 offset1:96
	v_mov_b32_e32 v4, v56
	v_mov_b32_e32 v5, v40
	v_mov_b32_e32 v18, v24
	s_waitcnt lgkmcnt(1)
	v_pk_fma_f32 v[4:5], v[4:5], v[84:85], v[2:3] op_sel_hi:[1,0,1] neg_lo:[0,0,1] neg_hi:[0,0,1]
	v_mov_b32_e32 v19, v8
	v_pk_mul_f32 v[20:21], v[4:5], v[4:5]
	s_waitcnt lgkmcnt(0)
	v_pk_fma_f32 v[2:3], v[18:19], v[84:85], v[6:7] op_sel_hi:[1,0,1] neg_lo:[0,0,1] neg_hi:[0,0,1]
	v_add_f32_e32 v1, v20, v21
	v_pk_mul_f32 v[6:7], v[2:3], v[2:3]
	s_nop 0
	v_add_f32_e32 v1, v1, v6
	v_add_f32_e32 v1, v1, v7
	v_mov_b32_e32 v7, s11
	s_waitcnt lgkmcnt(0)
	s_nop 1
	v_add_f32_dpp v1, v1, v1 quad_perm:[1,0,3,2] row_mask:0xf bank_mask:0xf
	s_waitcnt lgkmcnt(0)
	s_nop 1
	v_add_f32_dpp v1, v1, v1 quad_perm:[2,3,0,1] row_mask:0xf bank_mask:0xf
	s_waitcnt lgkmcnt(0)
	s_nop 1
	v_add_f32_dpp v1, v1, v1 row_half_mirror row_mask:0xf bank_mask:0xf
	s_waitcnt lgkmcnt(0)
	s_nop 1
	v_add_f32_dpp v1, v1, v1 row_mirror row_mask:0xf bank_mask:0xf
	ds_bpermute_b32 v6, v147, v1
	s_waitcnt lgkmcnt(0)
	v_add_f32_e32 v1, v1, v6
	v_fmamk_f32 v1, v1, 0x3c000000, v208
	v_mul_f32_e32 v6, 0x4b800000, v1
	v_cmp_gt_f32_e32 vcc, s95, v1
	s_nop 1
	v_cndmask_b32_e32 v1, v1, v6, vcc
	v_rsq_f32_e32 v1, v1
	s_nop 0
	v_mul_f32_e32 v6, 0x45800000, v1
	v_cndmask_b32_e32 v1, v1, v6, vcc
	v_or_b32_e32 v6, s10, v150
	v_lshlrev_b64 v[6:7], 11, v[6:7]
	v_lshl_add_u64 v[6:7], v[196:197], 0, v[6:7]
	v_mul_f32_e32 v212, v4, v1
	v_mul_f32_e32 v213, v5, v1
	s_nop 1
	v_mov_b32_dpp v214, v212 quad_perm:[1,0,3,2] row_mask:0xf bank_mask:0xf
	v_mov_b32_dpp v215, v213 quad_perm:[1,0,3,2] row_mask:0xf bank_mask:0xf
	v_cndmask_b32_e64 v212, v215, v212, s[6:7]
	v_cndmask_b32_e64 v213, v213, v214, s[6:7]
	v_cvt_pk_bf16_f32 v212, v212, v213
	global_store_dword v[6:7], v212, off
	v_mul_f32_e32 v213, v2, v1
	v_mul_f32_e32 v214, v3, v1
	s_nop 1
	v_mov_b32_dpp v215, v213 quad_perm:[1,0,3,2] row_mask:0xf bank_mask:0xf
	v_mov_b32_dpp v212, v214 quad_perm:[1,0,3,2] row_mask:0xf bank_mask:0xf
	v_cndmask_b32_e64 v213, v212, v213, s[6:7]
	v_cndmask_b32_e64 v214, v214, v215, s[6:7]
	v_cvt_pk_bf16_f32 v213, v213, v214
	global_store_dword v[6:7], v213, off offset:128
	s_waitcnt lgkmcnt(0)
	ds_read2_b32 v[2:3], v205 offset1:32
	ds_read2_b32 v[6:7], v205 offset0:64 offset1:96
	v_mov_b32_e32 v40, v57
	v_mov_b32_e32 v8, v25
	s_waitcnt lgkmcnt(1)
	v_pk_fma_f32 v[4:5], v[40:41], v[82:83], v[2:3] op_sel_hi:[1,0,1] neg_lo:[0,0,1] neg_hi:[0,0,1]
	s_waitcnt lgkmcnt(0)
	v_pk_fma_f32 v[2:3], v[8:9], v[82:83], v[6:7] op_sel_hi:[1,0,1] neg_lo:[0,0,1] neg_hi:[0,0,1]
	v_pk_mul_f32 v[6:7], v[4:5], v[4:5]
	v_pk_mul_f32 v[8:9], v[2:3], v[2:3]
	v_add_f32_e32 v1, v6, v7
	v_add_f32_e32 v1, v1, v8
	v_add_f32_e32 v1, v1, v9
	v_mov_b32_e32 v7, s11
	s_waitcnt lgkmcnt(0)
	s_nop 1
	v_add_f32_dpp v1, v1, v1 quad_perm:[1,0,3,2] row_mask:0xf bank_mask:0xf
	s_waitcnt lgkmcnt(0)
	s_nop 1
	v_add_f32_dpp v1, v1, v1 quad_perm:[2,3,0,1] row_mask:0xf bank_mask:0xf
	s_waitcnt lgkmcnt(0)
	s_nop 1
	v_add_f32_dpp v1, v1, v1 row_half_mirror row_mask:0xf bank_mask:0xf
	s_waitcnt lgkmcnt(0)
	s_nop 1
	v_add_f32_dpp v1, v1, v1 row_mirror row_mask:0xf bank_mask:0xf
	ds_bpermute_b32 v6, v147, v1
	s_waitcnt lgkmcnt(0)
	v_add_f32_e32 v1, v1, v6
	v_fmamk_f32 v1, v1, 0x3c000000, v208
	v_mul_f32_e32 v6, 0x4b800000, v1
	v_cmp_gt_f32_e32 vcc, s95, v1
	s_nop 1
	v_cndmask_b32_e32 v1, v1, v6, vcc
	v_rsq_f32_e32 v1, v1
	s_nop 0
	v_mul_f32_e32 v6, 0x45800000, v1
	v_cndmask_b32_e32 v1, v1, v6, vcc
	v_or_b32_e32 v6, s10, v152
	v_lshlrev_b64 v[6:7], 11, v[6:7]
	v_lshl_add_u64 v[6:7], v[196:197], 0, v[6:7]
	v_mul_f32_e32 v212, v4, v1
	v_mul_f32_e32 v213, v5, v1
	s_nop 1
	v_mov_b32_dpp v214, v212 quad_perm:[1,0,3,2] row_mask:0xf bank_mask:0xf
	v_mov_b32_dpp v215, v213 quad_perm:[1,0,3,2] row_mask:0xf bank_mask:0xf
	v_cndmask_b32_e64 v212, v215, v212, s[6:7]
	v_cndmask_b32_e64 v213, v213, v214, s[6:7]
	v_cvt_pk_bf16_f32 v212, v212, v213
	global_store_dword v[6:7], v212, off
	v_mul_f32_e32 v213, v2, v1
	v_mul_f32_e32 v214, v3, v1
	s_nop 1
	v_mov_b32_dpp v215, v213 quad_perm:[1,0,3,2] row_mask:0xf bank_mask:0xf
	v_mov_b32_dpp v212, v214 quad_perm:[1,0,3,2] row_mask:0xf bank_mask:0xf
	v_cndmask_b32_e64 v213, v212, v213, s[6:7]
	v_cndmask_b32_e64 v214, v214, v215, s[6:7]
	v_cvt_pk_bf16_f32 v213, v213, v214
	global_store_dword v[6:7], v213, off offset:128
	s_waitcnt lgkmcnt(0)
	ds_read2_b32 v[2:3], v216 offset1:32
	ds_read2_b32 v[6:7], v216 offset0:64 offset1:96
	v_mov_b32_e32 v4, v58
	v_mov_b32_e32 v5, v42
	v_mov_b32_e32 v8, v26
	s_waitcnt lgkmcnt(1)
	v_pk_fma_f32 v[4:5], v[4:5], v[80:81], v[2:3] op_sel_hi:[1,0,1] neg_lo:[0,0,1] neg_hi:[0,0,1]
	v_mov_b32_e32 v9, v10
	v_pk_mul_f32 v[18:19], v[4:5], v[4:5]
	s_waitcnt lgkmcnt(0)
	v_pk_fma_f32 v[2:3], v[8:9], v[80:81], v[6:7] op_sel_hi:[1,0,1] neg_lo:[0,0,1] neg_hi:[0,0,1]
	v_add_f32_e32 v1, v18, v19
	v_pk_mul_f32 v[6:7], v[2:3], v[2:3]
	s_nop 0
	v_add_f32_e32 v1, v1, v6
	v_add_f32_e32 v1, v1, v7
	v_mov_b32_e32 v7, s11
	s_waitcnt lgkmcnt(0)
	s_nop 1
	v_add_f32_dpp v1, v1, v1 quad_perm:[1,0,3,2] row_mask:0xf bank_mask:0xf
	s_waitcnt lgkmcnt(0)
	s_nop 1
	v_add_f32_dpp v1, v1, v1 quad_perm:[2,3,0,1] row_mask:0xf bank_mask:0xf
	s_waitcnt lgkmcnt(0)
	s_nop 1
	v_add_f32_dpp v1, v1, v1 row_half_mirror row_mask:0xf bank_mask:0xf
	s_waitcnt lgkmcnt(0)
	s_nop 1
	v_add_f32_dpp v1, v1, v1 row_mirror row_mask:0xf bank_mask:0xf
	ds_bpermute_b32 v6, v147, v1
	s_waitcnt lgkmcnt(0)
	v_add_f32_e32 v1, v1, v6
	v_fmamk_f32 v1, v1, 0x3c000000, v208
	v_mul_f32_e32 v6, 0x4b800000, v1
	v_cmp_gt_f32_e32 vcc, s95, v1
	s_nop 1
	v_cndmask_b32_e32 v1, v1, v6, vcc
	v_rsq_f32_e32 v1, v1
	s_nop 0
	v_mul_f32_e32 v6, 0x45800000, v1
	v_cndmask_b32_e32 v1, v1, v6, vcc
	v_or_b32_e32 v6, s10, v154
	v_lshlrev_b64 v[6:7], 11, v[6:7]
	v_lshl_add_u64 v[6:7], v[196:197], 0, v[6:7]
	v_mul_f32_e32 v212, v4, v1
	v_mul_f32_e32 v213, v5, v1
	s_nop 1
	v_mov_b32_dpp v214, v212 quad_perm:[1,0,3,2] row_mask:0xf bank_mask:0xf
	v_mov_b32_dpp v215, v213 quad_perm:[1,0,3,2] row_mask:0xf bank_mask:0xf
	v_cndmask_b32_e64 v212, v215, v212, s[6:7]
	v_cndmask_b32_e64 v213, v213, v214, s[6:7]
	v_cvt_pk_bf16_f32 v212, v212, v213
	global_store_dword v[6:7], v212, off
	v_mul_f32_e32 v213, v2, v1
	v_mul_f32_e32 v214, v3, v1
	s_nop 1
	v_mov_b32_dpp v215, v213 quad_perm:[1,0,3,2] row_mask:0xf bank_mask:0xf
	v_mov_b32_dpp v212, v214 quad_perm:[1,0,3,2] row_mask:0xf bank_mask:0xf
	v_cndmask_b32_e64 v213, v212, v213, s[6:7]
	v_cndmask_b32_e64 v214, v214, v215, s[6:7]
	v_cvt_pk_bf16_f32 v213, v213, v214
	global_store_dword v[6:7], v213, off offset:128
	s_waitcnt lgkmcnt(0)
	ds_read2_b32 v[2:3], v217 offset1:32
	ds_read2_b32 v[6:7], v217 offset0:64 offset1:96
	v_mov_b32_e32 v42, v59
	v_mov_b32_e32 v10, v27
	s_waitcnt lgkmcnt(1)
	v_pk_fma_f32 v[4:5], v[42:43], v[76:77], v[2:3] op_sel_hi:[1,0,1] neg_lo:[0,0,1] neg_hi:[0,0,1]
	s_waitcnt lgkmcnt(0)
	v_pk_fma_f32 v[2:3], v[10:11], v[76:77], v[6:7] op_sel_hi:[1,0,1] neg_lo:[0,0,1] neg_hi:[0,0,1]
	v_pk_mul_f32 v[6:7], v[4:5], v[4:5]
	v_pk_mul_f32 v[8:9], v[2:3], v[2:3]
	v_add_f32_e32 v1, v6, v7
	v_add_f32_e32 v1, v1, v8
	v_add_f32_e32 v1, v1, v9
	v_mov_b32_e32 v7, s11
	s_waitcnt lgkmcnt(0)
	s_nop 1
	v_add_f32_dpp v1, v1, v1 quad_perm:[1,0,3,2] row_mask:0xf bank_mask:0xf
	s_waitcnt lgkmcnt(0)
	s_nop 1
	v_add_f32_dpp v1, v1, v1 quad_perm:[2,3,0,1] row_mask:0xf bank_mask:0xf
	s_waitcnt lgkmcnt(0)
	s_nop 1
	v_add_f32_dpp v1, v1, v1 row_half_mirror row_mask:0xf bank_mask:0xf
	s_waitcnt lgkmcnt(0)
	s_nop 1
	v_add_f32_dpp v1, v1, v1 row_mirror row_mask:0xf bank_mask:0xf
	ds_bpermute_b32 v6, v147, v1
	s_waitcnt lgkmcnt(0)
	v_add_f32_e32 v1, v1, v6
	v_fmamk_f32 v1, v1, 0x3c000000, v208
	v_mul_f32_e32 v6, 0x4b800000, v1
	v_cmp_gt_f32_e32 vcc, s95, v1
	s_nop 1
	v_cndmask_b32_e32 v1, v1, v6, vcc
	v_rsq_f32_e32 v1, v1
	s_nop 0
	v_mul_f32_e32 v6, 0x45800000, v1
	v_cndmask_b32_e32 v1, v1, v6, vcc
	v_or_b32_e32 v6, s10, v156
	v_lshlrev_b64 v[6:7], 11, v[6:7]
	v_lshl_add_u64 v[6:7], v[196:197], 0, v[6:7]
	v_mul_f32_e32 v212, v4, v1
	v_mul_f32_e32 v213, v5, v1
	s_nop 1
	v_mov_b32_dpp v214, v212 quad_perm:[1,0,3,2] row_mask:0xf bank_mask:0xf
	v_mov_b32_dpp v215, v213 quad_perm:[1,0,3,2] row_mask:0xf bank_mask:0xf
	v_cndmask_b32_e64 v212, v215, v212, s[6:7]
	v_cndmask_b32_e64 v213, v213, v214, s[6:7]
	v_cvt_pk_bf16_f32 v212, v212, v213
	global_store_dword v[6:7], v212, off
	v_mul_f32_e32 v213, v2, v1
	v_mul_f32_e32 v214, v3, v1
	s_nop 1
	v_mov_b32_dpp v215, v213 quad_perm:[1,0,3,2] row_mask:0xf bank_mask:0xf
	v_mov_b32_dpp v212, v214 quad_perm:[1,0,3,2] row_mask:0xf bank_mask:0xf
	v_cndmask_b32_e64 v213, v212, v213, s[6:7]
	v_cndmask_b32_e64 v214, v214, v215, s[6:7]
	v_cvt_pk_bf16_f32 v213, v213, v214
	global_store_dword v[6:7], v213, off offset:128
	s_waitcnt lgkmcnt(0)
	ds_read2_b32 v[2:3], v218 offset1:32
	ds_read2_b32 v[6:7], v218 offset0:64 offset1:96
	v_mov_b32_e32 v4, v60
	v_mov_b32_e32 v5, v44
	v_mov_b32_e32 v8, v28
	s_waitcnt lgkmcnt(1)
	v_pk_fma_f32 v[4:5], v[4:5], v[72:73], v[2:3] op_sel_hi:[1,0,1] neg_lo:[0,0,1] neg_hi:[0,0,1]
	v_mov_b32_e32 v9, v12
	v_pk_mul_f32 v[10:11], v[4:5], v[4:5]
	s_waitcnt lgkmcnt(0)
	v_pk_fma_f32 v[2:3], v[8:9], v[72:73], v[6:7] op_sel_hi:[1,0,1] neg_lo:[0,0,1] neg_hi:[0,0,1]
	v_add_f32_e32 v1, v10, v11
	v_pk_mul_f32 v[6:7], v[2:3], v[2:3]
	s_nop 0
	v_add_f32_e32 v1, v1, v6
	v_add_f32_e32 v1, v1, v7
	v_mov_b32_e32 v7, s11
	s_waitcnt lgkmcnt(0)
	s_nop 1
	v_add_f32_dpp v1, v1, v1 quad_perm:[1,0,3,2] row_mask:0xf bank_mask:0xf
	s_waitcnt lgkmcnt(0)
	s_nop 1
	v_add_f32_dpp v1, v1, v1 quad_perm:[2,3,0,1] row_mask:0xf bank_mask:0xf
	s_waitcnt lgkmcnt(0)
	s_nop 1
	v_add_f32_dpp v1, v1, v1 row_half_mirror row_mask:0xf bank_mask:0xf
	s_waitcnt lgkmcnt(0)
	s_nop 1
	v_add_f32_dpp v1, v1, v1 row_mirror row_mask:0xf bank_mask:0xf
	ds_bpermute_b32 v6, v147, v1
	s_waitcnt lgkmcnt(0)
	v_add_f32_e32 v1, v1, v6
	v_fmamk_f32 v1, v1, 0x3c000000, v208
	v_mul_f32_e32 v6, 0x4b800000, v1
	v_cmp_gt_f32_e32 vcc, s95, v1
	s_nop 1
	v_cndmask_b32_e32 v1, v1, v6, vcc
	v_rsq_f32_e32 v1, v1
	s_nop 0
	v_mul_f32_e32 v6, 0x45800000, v1
	v_cndmask_b32_e32 v1, v1, v6, vcc
	v_or_b32_e32 v6, s10, v158
	v_lshlrev_b64 v[6:7], 11, v[6:7]
	v_lshl_add_u64 v[6:7], v[196:197], 0, v[6:7]
	v_mul_f32_e32 v212, v4, v1
	v_mul_f32_e32 v213, v5, v1
	s_nop 1
	v_mov_b32_dpp v214, v212 quad_perm:[1,0,3,2] row_mask:0xf bank_mask:0xf
	v_mov_b32_dpp v215, v213 quad_perm:[1,0,3,2] row_mask:0xf bank_mask:0xf
	v_cndmask_b32_e64 v212, v215, v212, s[6:7]
	v_cndmask_b32_e64 v213, v213, v214, s[6:7]
	v_cvt_pk_bf16_f32 v212, v212, v213
	global_store_dword v[6:7], v212, off
	v_mul_f32_e32 v213, v2, v1
	v_mul_f32_e32 v214, v3, v1
	s_nop 1
	v_mov_b32_dpp v215, v213 quad_perm:[1,0,3,2] row_mask:0xf bank_mask:0xf
	v_mov_b32_dpp v212, v214 quad_perm:[1,0,3,2] row_mask:0xf bank_mask:0xf
	v_cndmask_b32_e64 v213, v212, v213, s[6:7]
	v_cndmask_b32_e64 v214, v214, v215, s[6:7]
	v_cvt_pk_bf16_f32 v213, v213, v214
	global_store_dword v[6:7], v213, off offset:128
	s_waitcnt lgkmcnt(0)
	ds_read2_b32 v[2:3], v219 offset1:32
	ds_read2_b32 v[6:7], v219 offset0:64 offset1:96
	v_mov_b32_e32 v44, v61
	v_mov_b32_e32 v12, v29
	s_waitcnt lgkmcnt(1)
	v_pk_fma_f32 v[4:5], v[44:45], v[70:71], v[2:3] op_sel_hi:[1,0,1] neg_lo:[0,0,1] neg_hi:[0,0,1]
	s_waitcnt lgkmcnt(0)
	v_pk_fma_f32 v[2:3], v[12:13], v[70:71], v[6:7] op_sel_hi:[1,0,1] neg_lo:[0,0,1] neg_hi:[0,0,1]
	v_pk_mul_f32 v[6:7], v[4:5], v[4:5]
	v_pk_mul_f32 v[8:9], v[2:3], v[2:3]
	v_add_f32_e32 v1, v6, v7
	v_add_f32_e32 v1, v1, v8
	v_add_f32_e32 v1, v1, v9
	v_mov_b32_e32 v7, s11
	s_waitcnt lgkmcnt(0)
	s_nop 1
	v_add_f32_dpp v1, v1, v1 quad_perm:[1,0,3,2] row_mask:0xf bank_mask:0xf
	s_waitcnt lgkmcnt(0)
	s_nop 1
	v_add_f32_dpp v1, v1, v1 quad_perm:[2,3,0,1] row_mask:0xf bank_mask:0xf
	s_waitcnt lgkmcnt(0)
	s_nop 1
	v_add_f32_dpp v1, v1, v1 row_half_mirror row_mask:0xf bank_mask:0xf
	s_waitcnt lgkmcnt(0)
	s_nop 1
	v_add_f32_dpp v1, v1, v1 row_mirror row_mask:0xf bank_mask:0xf
	ds_bpermute_b32 v6, v147, v1
	s_waitcnt lgkmcnt(0)
	v_add_f32_e32 v1, v1, v6
	v_fmamk_f32 v1, v1, 0x3c000000, v208
	v_mul_f32_e32 v6, 0x4b800000, v1
	v_cmp_gt_f32_e32 vcc, s95, v1
	s_nop 1
	v_cndmask_b32_e32 v1, v1, v6, vcc
	v_rsq_f32_e32 v1, v1
	s_nop 0
	v_mul_f32_e32 v6, 0x45800000, v1
	v_cndmask_b32_e32 v1, v1, v6, vcc
	v_or_b32_e32 v6, s10, v160
	v_lshlrev_b64 v[6:7], 11, v[6:7]
	v_lshl_add_u64 v[6:7], v[196:197], 0, v[6:7]
	v_mul_f32_e32 v212, v4, v1
	v_mul_f32_e32 v213, v5, v1
	s_nop 1
	v_mov_b32_dpp v214, v212 quad_perm:[1,0,3,2] row_mask:0xf bank_mask:0xf
	v_mov_b32_dpp v215, v213 quad_perm:[1,0,3,2] row_mask:0xf bank_mask:0xf
	v_cndmask_b32_e64 v212, v215, v212, s[6:7]
	v_cndmask_b32_e64 v213, v213, v214, s[6:7]
	v_cvt_pk_bf16_f32 v212, v212, v213
	global_store_dword v[6:7], v212, off
	v_mul_f32_e32 v213, v2, v1
	v_mul_f32_e32 v214, v3, v1
	s_nop 1
	v_mov_b32_dpp v215, v213 quad_perm:[1,0,3,2] row_mask:0xf bank_mask:0xf
	v_mov_b32_dpp v212, v214 quad_perm:[1,0,3,2] row_mask:0xf bank_mask:0xf
	v_cndmask_b32_e64 v213, v212, v213, s[6:7]
	v_cndmask_b32_e64 v214, v214, v215, s[6:7]
	v_cvt_pk_bf16_f32 v213, v213, v214
	global_store_dword v[6:7], v213, off offset:128
	s_waitcnt lgkmcnt(0)
	ds_read2_b32 v[2:3], v220 offset1:32
	ds_read2_b32 v[6:7], v220 offset0:64 offset1:96
	v_mov_b32_e32 v4, v62
	v_mov_b32_e32 v5, v46
	v_mov_b32_e32 v8, v30
	s_waitcnt lgkmcnt(1)
	v_pk_fma_f32 v[4:5], v[4:5], v[78:79], v[2:3] op_sel_hi:[1,0,1] neg_lo:[0,0,1] neg_hi:[0,0,1]
	v_mov_b32_e32 v9, v14
	v_pk_mul_f32 v[10:11], v[4:5], v[4:5]
	s_waitcnt lgkmcnt(0)
	v_pk_fma_f32 v[2:3], v[8:9], v[78:79], v[6:7] op_sel_hi:[1,0,1] neg_lo:[0,0,1] neg_hi:[0,0,1]
	v_add_f32_e32 v1, v10, v11
	v_pk_mul_f32 v[6:7], v[2:3], v[2:3]
	s_nop 0
	v_add_f32_e32 v1, v1, v6
	v_add_f32_e32 v1, v1, v7
	v_mov_b32_e32 v7, s11
	s_waitcnt lgkmcnt(0)
	s_nop 1
	v_add_f32_dpp v1, v1, v1 quad_perm:[1,0,3,2] row_mask:0xf bank_mask:0xf
	s_waitcnt lgkmcnt(0)
	s_nop 1
	v_add_f32_dpp v1, v1, v1 quad_perm:[2,3,0,1] row_mask:0xf bank_mask:0xf
	s_waitcnt lgkmcnt(0)
	s_nop 1
	v_add_f32_dpp v1, v1, v1 row_half_mirror row_mask:0xf bank_mask:0xf
	s_waitcnt lgkmcnt(0)
	s_nop 1
	v_add_f32_dpp v1, v1, v1 row_mirror row_mask:0xf bank_mask:0xf
	ds_bpermute_b32 v6, v147, v1
	s_waitcnt lgkmcnt(0)
	v_add_f32_e32 v1, v1, v6
	v_fmamk_f32 v1, v1, 0x3c000000, v208
	v_mul_f32_e32 v6, 0x4b800000, v1
	v_cmp_gt_f32_e32 vcc, s95, v1
	s_nop 1
	v_cndmask_b32_e32 v1, v1, v6, vcc
	v_rsq_f32_e32 v1, v1
	s_nop 0
	v_mul_f32_e32 v6, 0x45800000, v1
	v_cndmask_b32_e32 v1, v1, v6, vcc
	v_or_b32_e32 v6, s10, v162
	v_lshlrev_b64 v[6:7], 11, v[6:7]
	v_lshl_add_u64 v[6:7], v[196:197], 0, v[6:7]
	v_mul_f32_e32 v212, v4, v1
	v_mul_f32_e32 v213, v5, v1
	s_nop 1
	v_mov_b32_dpp v214, v212 quad_perm:[1,0,3,2] row_mask:0xf bank_mask:0xf
	v_mov_b32_dpp v215, v213 quad_perm:[1,0,3,2] row_mask:0xf bank_mask:0xf
	v_cndmask_b32_e64 v212, v215, v212, s[6:7]
	v_cndmask_b32_e64 v213, v213, v214, s[6:7]
	v_cvt_pk_bf16_f32 v212, v212, v213
	global_store_dword v[6:7], v212, off
	v_mul_f32_e32 v213, v2, v1
	v_mul_f32_e32 v214, v3, v1
	s_nop 1
	v_mov_b32_dpp v215, v213 quad_perm:[1,0,3,2] row_mask:0xf bank_mask:0xf
	v_mov_b32_dpp v212, v214 quad_perm:[1,0,3,2] row_mask:0xf bank_mask:0xf
	v_cndmask_b32_e64 v213, v212, v213, s[6:7]
	v_cndmask_b32_e64 v214, v214, v215, s[6:7]
	v_cvt_pk_bf16_f32 v213, v213, v214
	global_store_dword v[6:7], v213, off offset:128
	s_waitcnt lgkmcnt(0)
	ds_read2_b32 v[2:3], v221 offset1:32
	ds_read2_b32 v[6:7], v221 offset0:64 offset1:96
	v_mov_b32_e32 v46, v63
	v_mov_b32_e32 v14, v31
	s_waitcnt lgkmcnt(1)
	v_pk_fma_f32 v[4:5], v[46:47], v[74:75], v[2:3] op_sel_hi:[1,0,1] neg_lo:[0,0,1] neg_hi:[0,0,1]
	s_waitcnt lgkmcnt(0)
	v_pk_fma_f32 v[2:3], v[14:15], v[74:75], v[6:7] op_sel_hi:[1,0,1] neg_lo:[0,0,1] neg_hi:[0,0,1]
	v_pk_mul_f32 v[6:7], v[4:5], v[4:5]
	v_pk_mul_f32 v[8:9], v[2:3], v[2:3]
	v_add_f32_e32 v1, v6, v7
	v_add_f32_e32 v1, v1, v8
	v_add_f32_e32 v1, v1, v9
	v_mov_b32_e32 v7, s11
	s_waitcnt lgkmcnt(0)
	s_nop 1
	v_add_f32_dpp v1, v1, v1 quad_perm:[1,0,3,2] row_mask:0xf bank_mask:0xf
	s_waitcnt lgkmcnt(0)
	s_nop 1
	v_add_f32_dpp v1, v1, v1 quad_perm:[2,3,0,1] row_mask:0xf bank_mask:0xf
	s_waitcnt lgkmcnt(0)
	s_nop 1
	v_add_f32_dpp v1, v1, v1 row_half_mirror row_mask:0xf bank_mask:0xf
	s_waitcnt lgkmcnt(0)
	s_nop 1
	v_add_f32_dpp v1, v1, v1 row_mirror row_mask:0xf bank_mask:0xf
	ds_bpermute_b32 v6, v147, v1
	s_waitcnt lgkmcnt(0)
	v_add_f32_e32 v1, v1, v6
	v_fmamk_f32 v1, v1, 0x3c000000, v208
	v_mul_f32_e32 v6, 0x4b800000, v1
	v_cmp_gt_f32_e32 vcc, s95, v1
	s_nop 1
	v_cndmask_b32_e32 v1, v1, v6, vcc
	v_rsq_f32_e32 v1, v1
	s_nop 0
	v_mul_f32_e32 v6, 0x45800000, v1
	v_cndmask_b32_e32 v1, v1, v6, vcc
	v_or_b32_e32 v6, s10, v164
	v_lshlrev_b64 v[6:7], 11, v[6:7]
	v_lshl_add_u64 v[6:7], v[196:197], 0, v[6:7]
	v_mul_f32_e32 v212, v4, v1
	v_mul_f32_e32 v213, v5, v1
	s_nop 1
	v_mov_b32_dpp v214, v212 quad_perm:[1,0,3,2] row_mask:0xf bank_mask:0xf
	v_mov_b32_dpp v215, v213 quad_perm:[1,0,3,2] row_mask:0xf bank_mask:0xf
	v_cndmask_b32_e64 v212, v215, v212, s[6:7]
	v_cndmask_b32_e64 v213, v213, v214, s[6:7]
	v_cvt_pk_bf16_f32 v212, v212, v213
	global_store_dword v[6:7], v212, off
	v_mul_f32_e32 v213, v2, v1
	v_mul_f32_e32 v214, v3, v1
	s_nop 1
	v_mov_b32_dpp v215, v213 quad_perm:[1,0,3,2] row_mask:0xf bank_mask:0xf
	v_mov_b32_dpp v212, v214 quad_perm:[1,0,3,2] row_mask:0xf bank_mask:0xf
	v_cndmask_b32_e64 v213, v212, v213, s[6:7]
	v_cndmask_b32_e64 v214, v214, v215, s[6:7]
	v_cvt_pk_bf16_f32 v213, v213, v214
	global_store_dword v[6:7], v213, off offset:128
	s_waitcnt lgkmcnt(0)
	ds_read2_b32 v[2:3], v222 offset1:32
	ds_read2_b32 v[6:7], v222 offset0:64 offset1:96
	v_mov_b32_e32 v4, v64
	v_mov_b32_e32 v5, v48
	v_mov_b32_e32 v8, v32
	s_waitcnt lgkmcnt(1)
	v_pk_fma_f32 v[4:5], v[4:5], v[68:69], v[2:3] op_sel_hi:[1,0,1] neg_lo:[0,0,1] neg_hi:[0,0,1]
	v_mov_b32_e32 v9, v16
	v_pk_mul_f32 v[10:11], v[4:5], v[4:5]
	s_waitcnt lgkmcnt(0)
	v_pk_fma_f32 v[2:3], v[8:9], v[68:69], v[6:7] op_sel_hi:[1,0,1] neg_lo:[0,0,1] neg_hi:[0,0,1]
	v_add_f32_e32 v1, v10, v11
	v_pk_mul_f32 v[6:7], v[2:3], v[2:3]
	s_nop 0
	v_add_f32_e32 v1, v1, v6
	v_add_f32_e32 v1, v1, v7
	v_mov_b32_e32 v7, s11
	s_waitcnt lgkmcnt(0)
	s_nop 1
	v_add_f32_dpp v1, v1, v1 quad_perm:[1,0,3,2] row_mask:0xf bank_mask:0xf
	s_waitcnt lgkmcnt(0)
	s_nop 1
	v_add_f32_dpp v1, v1, v1 quad_perm:[2,3,0,1] row_mask:0xf bank_mask:0xf
	s_waitcnt lgkmcnt(0)
	s_nop 1
	v_add_f32_dpp v1, v1, v1 row_half_mirror row_mask:0xf bank_mask:0xf
	s_waitcnt lgkmcnt(0)
	s_nop 1
	v_add_f32_dpp v1, v1, v1 row_mirror row_mask:0xf bank_mask:0xf
	ds_bpermute_b32 v6, v147, v1
	s_waitcnt lgkmcnt(0)
	v_add_f32_e32 v1, v1, v6
	v_fmamk_f32 v1, v1, 0x3c000000, v208
	v_mul_f32_e32 v6, 0x4b800000, v1
	v_cmp_gt_f32_e32 vcc, s95, v1
	s_nop 1
	v_cndmask_b32_e32 v1, v1, v6, vcc
	v_rsq_f32_e32 v1, v1
	s_nop 0
	v_mul_f32_e32 v6, 0x45800000, v1
	v_cndmask_b32_e32 v1, v1, v6, vcc
	v_or_b32_e32 v6, s10, v166
	v_lshlrev_b64 v[6:7], 11, v[6:7]
	v_lshl_add_u64 v[6:7], v[196:197], 0, v[6:7]
	v_mul_f32_e32 v212, v4, v1
	v_mul_f32_e32 v213, v5, v1
	s_nop 1
	v_mov_b32_dpp v214, v212 quad_perm:[1,0,3,2] row_mask:0xf bank_mask:0xf
	v_mov_b32_dpp v215, v213 quad_perm:[1,0,3,2] row_mask:0xf bank_mask:0xf
	v_cndmask_b32_e64 v212, v215, v212, s[6:7]
	v_cndmask_b32_e64 v213, v213, v214, s[6:7]
	v_cvt_pk_bf16_f32 v212, v212, v213
	global_store_dword v[6:7], v212, off
	v_mul_f32_e32 v213, v2, v1
	v_mul_f32_e32 v214, v3, v1
	s_nop 1
	v_mov_b32_dpp v215, v213 quad_perm:[1,0,3,2] row_mask:0xf bank_mask:0xf
	v_mov_b32_dpp v212, v214 quad_perm:[1,0,3,2] row_mask:0xf bank_mask:0xf
	v_cndmask_b32_e64 v213, v212, v213, s[6:7]
	v_cndmask_b32_e64 v214, v214, v215, s[6:7]
	v_cvt_pk_bf16_f32 v213, v213, v214
	global_store_dword v[6:7], v213, off offset:128
	s_waitcnt lgkmcnt(0)
	ds_read2_b32 v[2:3], v223 offset1:32
	ds_read2_b32 v[4:5], v223 offset0:64 offset1:96
	v_mov_b32_e32 v48, v65
	v_mov_b32_e32 v16, v33
	s_waitcnt lgkmcnt(1)
	v_pk_fma_f32 v[2:3], v[48:49], v[66:67], v[2:3] op_sel_hi:[1,0,1] neg_lo:[0,0,1] neg_hi:[0,0,1]
	s_nop 0
	v_pk_mul_f32 v[6:7], v[2:3], v[2:3]
	s_waitcnt lgkmcnt(0)
	v_pk_fma_f32 v[4:5], v[16:17], v[66:67], v[4:5] op_sel_hi:[1,0,1] neg_lo:[0,0,1] neg_hi:[0,0,1]
	v_add_f32_e32 v1, v6, v7
	v_pk_mul_f32 v[8:9], v[4:5], v[4:5]
	v_mov_b32_e32 v7, s11
	v_add_f32_e32 v1, v1, v8
	v_add_f32_e32 v1, v1, v9
	s_waitcnt lgkmcnt(0)
	s_nop 1
	v_add_f32_dpp v1, v1, v1 quad_perm:[1,0,3,2] row_mask:0xf bank_mask:0xf
	s_waitcnt lgkmcnt(0)
	s_nop 1
	v_add_f32_dpp v1, v1, v1 quad_perm:[2,3,0,1] row_mask:0xf bank_mask:0xf
	s_waitcnt lgkmcnt(0)
	s_nop 1
	v_add_f32_dpp v1, v1, v1 row_half_mirror row_mask:0xf bank_mask:0xf
	s_waitcnt lgkmcnt(0)
	s_nop 1
	v_add_f32_dpp v1, v1, v1 row_mirror row_mask:0xf bank_mask:0xf
	ds_bpermute_b32 v6, v147, v1
	s_waitcnt lgkmcnt(0)
	v_add_f32_e32 v1, v1, v6
	v_fmamk_f32 v1, v1, 0x3c000000, v208
	v_cmp_gt_f32_e32 vcc, s95, v1
	v_mul_f32_e32 v6, 0x4b800000, v1
	s_nop 0
	v_cndmask_b32_e32 v1, v1, v6, vcc
	v_rsq_f32_e32 v1, v1
	s_nop 0
	v_mul_f32_e32 v6, 0x45800000, v1
	v_cndmask_b32_e32 v1, v1, v6, vcc
	v_or_b32_e32 v6, s10, v168
	v_lshlrev_b64 v[6:7], 11, v[6:7]
	v_lshl_add_u64 v[6:7], v[196:197], 0, v[6:7]
	v_mul_f32_e32 v212, v2, v1
	v_mul_f32_e32 v213, v3, v1
	s_nop 1
	v_mov_b32_dpp v214, v212 quad_perm:[1,0,3,2] row_mask:0xf bank_mask:0xf
	v_mov_b32_dpp v215, v213 quad_perm:[1,0,3,2] row_mask:0xf bank_mask:0xf
	v_cndmask_b32_e64 v212, v215, v212, s[6:7]
	v_cndmask_b32_e64 v213, v213, v214, s[6:7]
	v_cvt_pk_bf16_f32 v212, v212, v213
	global_store_dword v[6:7], v212, off
	v_mul_f32_e32 v213, v4, v1
	v_mul_f32_e32 v214, v5, v1
	s_nop 1
	v_mov_b32_dpp v215, v213 quad_perm:[1,0,3,2] row_mask:0xf bank_mask:0xf
	v_mov_b32_dpp v212, v214 quad_perm:[1,0,3,2] row_mask:0xf bank_mask:0xf
	v_cndmask_b32_e64 v213, v212, v213, s[6:7]
	v_cndmask_b32_e64 v214, v214, v215, s[6:7]
	v_cvt_pk_bf16_f32 v213, v213, v214
	global_store_dword v[6:7], v213, off offset:128
	s_branch .LBB0_161
